# lever 9 loop-edge: renormalisation check rotated from the loop head into the tail of the sixth tile (head starts with the K fragment reads)
# speedup vs baseline: 1.0051x; 1.0051x over previous
; #define AT_QK_LD0(kb_) do { if constexpr (NEGM) { const LAS unsigned char* kbp_ = Kl + (kb_) * KBUF + r32 * KROWB + hi * 16; AT_KLD2(0); __builtin_amdgcn_sched_barrier(0); } } while (0)
; template <int DQK, int DV, int RH, bool NEGM> ...
;     ...
;         for (int t = 0; t < NT; ++t) {
;             const int kb = t & 1;
;             if (t + 1 < NT) AT_GLOAD(t + 1);
;             f32x16 p[RH][2];
;             AT_QK_LD0(kb); AT_QK(kb); AT_VLOAD(vs_cur); AT_SOFTMAX(); AT_PV(vs_cur);
;             if (t + 1 < NT) AT_LSTORE(kb ^ 1, vs_next);
;             __syncthreads();
;             vs_prev = vs_cur; vs_cur = vs_next; vs_next = (vs_next == 2) ? 0 : vs_next + 1;
.Lmla_loop:
	ds_read_b128 v[48:51], v169 offset:13312
	ds_read_b128 v[52:55], v169 offset:13344
	ds_read_b128 v[116:119], v169 offset:19968
	ds_read_b128 v[120:123], v169 offset:20000
	s_mov_b32 m0, s70
	s_nop 0
	global_load_lds_dwordx4 v241, s[98:99]
	s_mov_b32 m0, s73
	global_load_dwordx4 v[112:115], v158, s[100:101]
	global_load_lds_dwordx4 v242, s[98:99]
	s_add_u32 s98, s98, 0x18000
	s_addc_u32 s99, s99, 0
	s_waitcnt lgkmcnt(3)
	v_mfma_f32_32x32x16_bf16 v[64:79], v[48:51], v[100:103], v[32:47]
	ds_read_b128 v[124:127], v169 offset:13376
	ds_read_b128 v[128:131], v169 offset:13408
	ds_read_b128 v[132:135], v169 offset:20032
	ds_read_b128 v[136:139], v169 offset:20064
	s_waitcnt lgkmcnt(4)
	v_mfma_f32_32x32x16_bf16 v[64:79], v[52:55], v[96:99], v[64:79]
	v_mfma_f32_32x32x16_bf16 v[48:63], v[116:119], v[100:103], v[32:47]
	v_mfma_f32_32x32x16_bf16 v[48:63], v[120:123], v[96:99], v[48:63]
	s_waitcnt lgkmcnt(1)
	v_mfma_f32_32x32x16_bf16 v[64:79], v[124:127], v[92:95], v[64:79]
	v_mfma_f32_32x32x16_bf16 v[48:63], v[132:135], v[92:95], v[48:63]
	v_mfma_f32_32x32x16_bf16 v[64:79], v[128:131], v[88:91], v[64:79]
	ds_read_b128 v[116:119], v169 offset:13440
	ds_read_b128 v[120:123], v169 offset:13472
	ds_read_b128 v[128:131], v169 offset:20096
	ds_read_b128 v[176:179], v169 offset:20128
	s_waitcnt lgkmcnt(3)
	v_mfma_f32_32x32x16_bf16 v[48:63], v[136:139], v[88:91], v[48:63]
	v_mfma_f32_32x32x16_bf16 v[64:79], v[116:119], v[84:87], v[64:79]
	ds_read_b128 v[136:139], v170 offset:35840
	ds_read_b128 v[124:127], v170 offset:35872
	s_waitcnt lgkmcnt(3)
	v_mfma_f32_32x32x16_bf16 v[48:63], v[128:131], v[84:87], v[48:63]
	v_mfma_f32_32x32x16_bf16 v[64:79], v[120:123], v[80:83], v[64:79]
	ds_read_b128 v[132:135], v170 offset:35904
	ds_read_b128 v[120:123], v170 offset:35936
	ds_read_b128 v[144:147], v170 offset:40448
	ds_read_b128 v[140:143], v170 offset:40480
	ds_read_b128 v[128:131], v170 offset:40512
	ds_read_b128 v[116:119], v170 offset:40544
	s_waitcnt lgkmcnt(8)
	v_mfma_f32_32x32x16_bf16 v[48:63], v[176:179], v[80:83], v[48:63]
	s_add_i32 s43, s43, 1
	s_nop 3
	v_exp_f32_e32 v160, v64
	v_exp_f32_e32 v161, v65
	v_exp_f32_e32 v64, v66
	v_exp_f32_e32 v65, v67
	v_exp_f32_e32 v68, v68
	v_exp_f32_e32 v69, v69
	v_exp_f32_e32 v66, v70
	v_exp_f32_e32 v67, v71
	v_cvt_pk_bf16_f32 v176, v160, v161
	v_cvt_pk_bf16_f32 v177, v64, v65
	v_cvt_pk_bf16_f32 v178, v68, v69
	v_cvt_pk_bf16_f32 v179, v66, v67
	v_exp_f32_e32 v70, v74
	v_exp_f32_e32 v71, v75
	s_waitcnt lgkmcnt(0)
	v_mfma_f32_32x32x16_bf16 v[16:31], v[136:139], v[176:179], v[16:31]
	v_exp_f32_e32 v136, v72
	v_exp_f32_e32 v137, v73
	v_exp_f32_e32 v74, v76
	v_exp_f32_e32 v75, v77
	v_exp_f32_e32 v72, v78
	v_exp_f32_e32 v73, v79
	v_exp_f32_e32 v76, v48
	v_mfma_f32_32x32x16_bf16 v[0:15], v[144:147], v[176:179], v[0:15]
	v_cvt_pk_bf16_f32 v144, v136, v137
	v_cvt_pk_bf16_f32 v145, v70, v71
	v_cvt_pk_bf16_f32 v146, v74, v75
	v_cvt_pk_bf16_f32 v147, v72, v73
	v_exp_f32_e32 v77, v49
	v_exp_f32_e32 v48, v50
	v_exp_f32_e32 v49, v51
	v_mfma_f32_32x32x16_bf16 v[16:31], v[124:127], v[144:147], v[16:31]
	v_exp_f32_e32 v52, v52
	v_exp_f32_e32 v53, v53
	v_exp_f32_e32 v50, v54
	v_exp_f32_e32 v51, v55
	v_cvt_pk_bf16_f32 v124, v76, v77
	v_cvt_pk_bf16_f32 v125, v48, v49
	v_cvt_pk_bf16_f32 v126, v52, v53
	v_mfma_f32_32x32x16_bf16 v[0:15], v[140:143], v[144:147], v[0:15]
	v_cvt_pk_bf16_f32 v127, v50, v51
	v_exp_f32_e32 v78, v56
	v_exp_f32_e32 v79, v57
	v_exp_f32_e32 v54, v58
	v_exp_f32_e32 v55, v59
	v_exp_f32_e32 v58, v60
	v_exp_f32_e32 v59, v61
	v_mfma_f32_32x32x16_bf16 v[16:31], v[132:135], v[124:127], v[16:31]
	v_exp_f32_e32 v56, v62
	v_exp_f32_e32 v57, v63
	v_cvt_pk_bf16_f32 v60, v78, v79
	v_cvt_pk_bf16_f32 v61, v54, v55
	v_cvt_pk_bf16_f32 v62, v58, v59
	v_cvt_pk_bf16_f32 v63, v56, v57
	v_mfma_f32_32x32x16_bf16 v[0:15], v[128:131], v[124:127], v[0:15]
	v_mfma_f32_32x32x16_bf16 v[16:31], v[120:123], v[60:63], v[16:31]
	v_mfma_f32_32x32x16_bf16 v[0:15], v[116:119], v[60:63], v[0:15]
	s_waitcnt vmcnt(0)
	ds_write2_b64 v247, v[112:113], v[114:115] offset1:2
	v_pk_add_f32 v[48:49], v[64:65], v[48:49]
	v_pk_add_f32 v[60:61], v[160:161], v[76:77]
	v_pk_add_f32 v[48:49], v[152:153], v[48:49]
	v_pk_add_f32 v[50:51], v[66:67], v[50:51]
	v_pk_add_f32 v[60:61], v[150:151], v[60:61]
	v_pk_add_f32 v[52:53], v[68:69], v[52:53]
	v_pk_add_f32 v[48:49], v[50:51], v[48:49]
	v_pk_add_f32 v[50:51], v[70:71], v[54:55]
	v_pk_add_f32 v[52:53], v[52:53], v[60:61]
	v_pk_add_f32 v[60:61], v[136:137], v[78:79]
	v_pk_add_f32 v[48:49], v[50:51], v[48:49]
	v_pk_add_f32 v[50:51], v[72:73], v[56:57]
	v_pk_add_f32 v[52:53], v[60:61], v[52:53]
	v_pk_add_f32 v[58:59], v[74:75], v[58:59]
	v_pk_add_f32 v[152:153], v[50:51], v[48:49]
	v_pk_add_f32 v[150:151], v[58:59], v[52:53]
	s_waitcnt lgkmcnt(0)
	s_barrier
; #define AT_QK_LD0(kb_) do { if constexpr (NEGM) { const LAS unsigned char* kbp_ = Kl + (kb_) * KBUF + r32 * KROWB + hi * 16; AT_KLD2(0); __builtin_amdgcn_sched_barrier(0); } } while (0)
; template <int DQK, int DV, int RH, bool NEGM> ...
;     ...
;         for (int t = 0; t < NT; ++t) {
;             const int kb = t & 1;
;             if (t + 1 < NT) AT_GLOAD(t + 1);
;             f32x16 p[RH][2];
;             AT_QK_LD0(kb); AT_QK(kb); AT_VLOAD(vs_cur); AT_SOFTMAX(); AT_PV(vs_cur);
;             if (t + 1 < NT) AT_LSTORE(kb ^ 1, vs_next);
;             __syncthreads();
;             vs_prev = vs_cur; vs_cur = vs_next; vs_next = (vs_next == 2) ? 0 : vs_next + 1;
	ds_read_b128 v[48:51], v169
	ds_read_b128 v[52:55], v169 offset:32
	ds_read_b128 v[116:119], v169 offset:6656
	ds_read_b128 v[120:123], v169 offset:6688
	s_add_i32 m0, s70, 13312
	s_nop 0
	global_load_lds_dwordx4 v241, s[98:99]
	s_add_i32 m0, s73, s74
	global_load_dwordx4 v[112:115], v158, s[100:101] offset:128
	global_load_lds_dwordx4 v242, s[98:99]
	s_add_u32 s98, s98, 0x18000
	s_addc_u32 s99, s99, 0
	s_waitcnt lgkmcnt(3)
	v_mfma_f32_32x32x16_bf16 v[64:79], v[48:51], v[100:103], v[32:47]
	ds_read_b128 v[124:127], v169 offset:64
	ds_read_b128 v[128:131], v169 offset:96
	ds_read_b128 v[132:135], v169 offset:6720
	ds_read_b128 v[136:139], v169 offset:6752
	s_waitcnt lgkmcnt(4)
	v_mfma_f32_32x32x16_bf16 v[64:79], v[52:55], v[96:99], v[64:79]
	v_mfma_f32_32x32x16_bf16 v[48:63], v[116:119], v[100:103], v[32:47]
	v_mfma_f32_32x32x16_bf16 v[48:63], v[120:123], v[96:99], v[48:63]
	s_waitcnt lgkmcnt(1)
	v_mfma_f32_32x32x16_bf16 v[64:79], v[124:127], v[92:95], v[64:79]
	v_mfma_f32_32x32x16_bf16 v[48:63], v[132:135], v[92:95], v[48:63]
	v_mfma_f32_32x32x16_bf16 v[64:79], v[128:131], v[88:91], v[64:79]
	ds_read_b128 v[116:119], v169 offset:128
	ds_read_b128 v[120:123], v169 offset:160
	ds_read_b128 v[128:131], v169 offset:6784
	ds_read_b128 v[176:179], v169 offset:6816
	s_waitcnt lgkmcnt(3)
	v_mfma_f32_32x32x16_bf16 v[48:63], v[136:139], v[88:91], v[48:63]
	v_mfma_f32_32x32x16_bf16 v[64:79], v[116:119], v[84:87], v[64:79]
	ds_read_b128 v[136:139], v170 offset:45056
	ds_read_b128 v[124:127], v170 offset:45088
	s_waitcnt lgkmcnt(3)
	v_mfma_f32_32x32x16_bf16 v[48:63], v[128:131], v[84:87], v[48:63]
	v_mfma_f32_32x32x16_bf16 v[64:79], v[120:123], v[80:83], v[64:79]
	ds_read_b128 v[132:135], v170 offset:45120
	ds_read_b128 v[120:123], v170 offset:45152
	ds_read_b128 v[144:147], v170 offset:49664
	ds_read_b128 v[140:143], v170 offset:49696
	ds_read_b128 v[128:131], v170 offset:49728
	ds_read_b128 v[116:119], v170 offset:49760
	s_waitcnt lgkmcnt(8)
	v_mfma_f32_32x32x16_bf16 v[48:63], v[176:179], v[80:83], v[48:63]
	s_add_i32 s43, s43, 1
	s_nop 3
	v_exp_f32_e32 v160, v64
	v_exp_f32_e32 v161, v65
	v_exp_f32_e32 v64, v66
	v_exp_f32_e32 v65, v67
	v_exp_f32_e32 v68, v68
	v_exp_f32_e32 v69, v69
	v_exp_f32_e32 v66, v70
	v_exp_f32_e32 v67, v71
	v_cvt_pk_bf16_f32 v176, v160, v161
	v_cvt_pk_bf16_f32 v177, v64, v65
	v_cvt_pk_bf16_f32 v178, v68, v69
	v_cvt_pk_bf16_f32 v179, v66, v67
	v_exp_f32_e32 v70, v74
	v_exp_f32_e32 v71, v75
	s_waitcnt lgkmcnt(0)
	v_mfma_f32_32x32x16_bf16 v[16:31], v[136:139], v[176:179], v[16:31]
	v_exp_f32_e32 v136, v72
	v_exp_f32_e32 v137, v73
	v_exp_f32_e32 v74, v76
	v_exp_f32_e32 v75, v77
	v_exp_f32_e32 v72, v78
	v_exp_f32_e32 v73, v79
	v_exp_f32_e32 v76, v48
	v_mfma_f32_32x32x16_bf16 v[0:15], v[144:147], v[176:179], v[0:15]
	v_cvt_pk_bf16_f32 v144, v136, v137
	v_cvt_pk_bf16_f32 v145, v70, v71
	v_cvt_pk_bf16_f32 v146, v74, v75
	v_cvt_pk_bf16_f32 v147, v72, v73
	v_exp_f32_e32 v77, v49
	v_exp_f32_e32 v48, v50
	v_exp_f32_e32 v49, v51
	v_mfma_f32_32x32x16_bf16 v[16:31], v[124:127], v[144:147], v[16:31]
	v_exp_f32_e32 v52, v52
	v_exp_f32_e32 v53, v53
	v_exp_f32_e32 v50, v54
	v_exp_f32_e32 v51, v55
	v_cvt_pk_bf16_f32 v124, v76, v77
	v_cvt_pk_bf16_f32 v125, v48, v49
	v_cvt_pk_bf16_f32 v126, v52, v53
	v_mfma_f32_32x32x16_bf16 v[0:15], v[140:143], v[144:147], v[0:15]
	v_cvt_pk_bf16_f32 v127, v50, v51
	v_exp_f32_e32 v78, v56
	v_exp_f32_e32 v79, v57
	v_exp_f32_e32 v54, v58
	v_exp_f32_e32 v55, v59
	v_exp_f32_e32 v58, v60
	v_exp_f32_e32 v59, v61
	v_mfma_f32_32x32x16_bf16 v[16:31], v[132:135], v[124:127], v[16:31]
	v_exp_f32_e32 v56, v62
	v_exp_f32_e32 v57, v63
	v_cvt_pk_bf16_f32 v60, v78, v79
	v_cvt_pk_bf16_f32 v61, v54, v55
	v_cvt_pk_bf16_f32 v62, v58, v59
	v_cvt_pk_bf16_f32 v63, v56, v57
	v_mfma_f32_32x32x16_bf16 v[0:15], v[128:131], v[124:127], v[0:15]
	v_mfma_f32_32x32x16_bf16 v[16:31], v[120:123], v[60:63], v[16:31]
	v_mfma_f32_32x32x16_bf16 v[0:15], v[116:119], v[60:63], v[0:15]
	s_waitcnt vmcnt(0)
	ds_write2_b64 v243, v[112:113], v[114:115] offset1:2
	v_pk_add_f32 v[48:49], v[64:65], v[48:49]
	v_pk_add_f32 v[60:61], v[160:161], v[76:77]
	v_pk_add_f32 v[48:49], v[152:153], v[48:49]
	v_pk_add_f32 v[50:51], v[66:67], v[50:51]
	v_pk_add_f32 v[60:61], v[150:151], v[60:61]
	v_pk_add_f32 v[52:53], v[68:69], v[52:53]
	v_pk_add_f32 v[48:49], v[50:51], v[48:49]
	v_pk_add_f32 v[50:51], v[70:71], v[54:55]
	v_pk_add_f32 v[52:53], v[52:53], v[60:61]
	v_pk_add_f32 v[60:61], v[136:137], v[78:79]
	v_pk_add_f32 v[48:49], v[50:51], v[48:49]
	v_pk_add_f32 v[50:51], v[72:73], v[56:57]
	v_pk_add_f32 v[52:53], v[60:61], v[52:53]
	v_pk_add_f32 v[58:59], v[74:75], v[58:59]
	v_pk_add_f32 v[152:153], v[50:51], v[48:49]
	v_pk_add_f32 v[150:151], v[58:59], v[52:53]
	s_cmp_lg_u32 s43, 63
	s_waitcnt lgkmcnt(0)
	s_barrier
	s_cbranch_scc0 .Lmla_exit
; #define AT_QK_LD0(kb_) do { if constexpr (NEGM) { const LAS unsigned char* kbp_ = Kl + (kb_) * KBUF + r32 * KROWB + hi * 16; AT_KLD2(0); __builtin_amdgcn_sched_barrier(0); } } while (0)
; template <int DQK, int DV, int RH, bool NEGM> ...
;     ...
;         for (int t = 0; t < NT; ++t) {
;             const int kb = t & 1;
;             if (t + 1 < NT) AT_GLOAD(t + 1);
;             f32x16 p[RH][2];
;             AT_QK_LD0(kb); AT_QK(kb); AT_VLOAD(vs_cur); AT_SOFTMAX(); AT_PV(vs_cur);
;             if (t + 1 < NT) AT_LSTORE(kb ^ 1, vs_next);
;             __syncthreads();
;             vs_prev = vs_cur; vs_cur = vs_next; vs_next = (vs_next == 2) ? 0 : vs_next + 1;
	ds_read_b128 v[48:51], v169 offset:13312
	ds_read_b128 v[52:55], v169 offset:13344
	ds_read_b128 v[116:119], v169 offset:19968
	ds_read_b128 v[120:123], v169 offset:20000
	s_mov_b32 m0, s70
	s_nop 0
	global_load_lds_dwordx4 v241, s[98:99]
	s_mov_b32 m0, s73
	global_load_dwordx4 v[112:115], v158, s[100:101] offset:256
	global_load_lds_dwordx4 v242, s[98:99]
	s_add_u32 s98, s98, 0x18000
	s_addc_u32 s99, s99, 0
	s_waitcnt lgkmcnt(3)
	v_mfma_f32_32x32x16_bf16 v[64:79], v[48:51], v[100:103], v[32:47]
	ds_read_b128 v[124:127], v169 offset:13376
	ds_read_b128 v[128:131], v169 offset:13408
	ds_read_b128 v[132:135], v169 offset:20032
	ds_read_b128 v[136:139], v169 offset:20064
	s_waitcnt lgkmcnt(4)
	v_mfma_f32_32x32x16_bf16 v[64:79], v[52:55], v[96:99], v[64:79]
	v_mfma_f32_32x32x16_bf16 v[48:63], v[116:119], v[100:103], v[32:47]
	v_mfma_f32_32x32x16_bf16 v[48:63], v[120:123], v[96:99], v[48:63]
	s_waitcnt lgkmcnt(1)
	v_mfma_f32_32x32x16_bf16 v[64:79], v[124:127], v[92:95], v[64:79]
	v_mfma_f32_32x32x16_bf16 v[48:63], v[132:135], v[92:95], v[48:63]
	v_mfma_f32_32x32x16_bf16 v[64:79], v[128:131], v[88:91], v[64:79]
	ds_read_b128 v[116:119], v169 offset:13440
	ds_read_b128 v[120:123], v169 offset:13472
	ds_read_b128 v[128:131], v169 offset:20096
	ds_read_b128 v[176:179], v169 offset:20128
	s_waitcnt lgkmcnt(3)
	v_mfma_f32_32x32x16_bf16 v[48:63], v[136:139], v[88:91], v[48:63]
	v_mfma_f32_32x32x16_bf16 v[64:79], v[116:119], v[84:87], v[64:79]
	ds_read_b128 v[136:139], v170 offset:26624
	ds_read_b128 v[124:127], v170 offset:26656
	s_waitcnt lgkmcnt(3)
	v_mfma_f32_32x32x16_bf16 v[48:63], v[128:131], v[84:87], v[48:63]
	v_mfma_f32_32x32x16_bf16 v[64:79], v[120:123], v[80:83], v[64:79]
	ds_read_b128 v[132:135], v170 offset:26688
	ds_read_b128 v[120:123], v170 offset:26720
	ds_read_b128 v[144:147], v170 offset:31232
	ds_read_b128 v[140:143], v170 offset:31264
	ds_read_b128 v[128:131], v170 offset:31296
	ds_read_b128 v[116:119], v170 offset:31328
	s_waitcnt lgkmcnt(8)
	v_mfma_f32_32x32x16_bf16 v[48:63], v[176:179], v[80:83], v[48:63]
	s_add_i32 s43, s43, 1
	s_nop 3
	v_exp_f32_e32 v160, v64
	v_exp_f32_e32 v161, v65
	v_exp_f32_e32 v64, v66
	v_exp_f32_e32 v65, v67
	v_exp_f32_e32 v68, v68
	v_exp_f32_e32 v69, v69
	v_exp_f32_e32 v66, v70
	v_exp_f32_e32 v67, v71
	v_cvt_pk_bf16_f32 v176, v160, v161
	v_cvt_pk_bf16_f32 v177, v64, v65
	v_cvt_pk_bf16_f32 v178, v68, v69
	v_cvt_pk_bf16_f32 v179, v66, v67
	v_exp_f32_e32 v70, v74
	v_exp_f32_e32 v71, v75
	s_waitcnt lgkmcnt(0)
	v_mfma_f32_32x32x16_bf16 v[16:31], v[136:139], v[176:179], v[16:31]
	v_exp_f32_e32 v136, v72
	v_exp_f32_e32 v137, v73
	v_exp_f32_e32 v74, v76
	v_exp_f32_e32 v75, v77
	v_exp_f32_e32 v72, v78
	v_exp_f32_e32 v73, v79
	v_exp_f32_e32 v76, v48
	v_mfma_f32_32x32x16_bf16 v[0:15], v[144:147], v[176:179], v[0:15]
	v_cvt_pk_bf16_f32 v144, v136, v137
	v_cvt_pk_bf16_f32 v145, v70, v71
	v_cvt_pk_bf16_f32 v146, v74, v75
	v_cvt_pk_bf16_f32 v147, v72, v73
	v_exp_f32_e32 v77, v49
	v_exp_f32_e32 v48, v50
	v_exp_f32_e32 v49, v51
	v_mfma_f32_32x32x16_bf16 v[16:31], v[124:127], v[144:147], v[16:31]
	v_exp_f32_e32 v52, v52
	v_exp_f32_e32 v53, v53
	v_exp_f32_e32 v50, v54
	v_exp_f32_e32 v51, v55
	v_cvt_pk_bf16_f32 v124, v76, v77
	v_cvt_pk_bf16_f32 v125, v48, v49
	v_cvt_pk_bf16_f32 v126, v52, v53
	v_mfma_f32_32x32x16_bf16 v[0:15], v[140:143], v[144:147], v[0:15]
	v_cvt_pk_bf16_f32 v127, v50, v51
	v_exp_f32_e32 v78, v56
	v_exp_f32_e32 v79, v57
	v_exp_f32_e32 v54, v58
	v_exp_f32_e32 v55, v59
	v_exp_f32_e32 v58, v60
	v_exp_f32_e32 v59, v61
	v_mfma_f32_32x32x16_bf16 v[16:31], v[132:135], v[124:127], v[16:31]
	v_exp_f32_e32 v56, v62
	v_exp_f32_e32 v57, v63
	v_cvt_pk_bf16_f32 v60, v78, v79
	v_cvt_pk_bf16_f32 v61, v54, v55
	v_cvt_pk_bf16_f32 v62, v58, v59
	v_cvt_pk_bf16_f32 v63, v56, v57
	v_mfma_f32_32x32x16_bf16 v[0:15], v[128:131], v[124:127], v[0:15]
	v_mfma_f32_32x32x16_bf16 v[16:31], v[120:123], v[60:63], v[16:31]
	v_mfma_f32_32x32x16_bf16 v[0:15], v[116:119], v[60:63], v[0:15]
	s_waitcnt vmcnt(0)
	ds_write2_b64 v246, v[112:113], v[114:115] offset1:2
	v_pk_add_f32 v[48:49], v[64:65], v[48:49]
	v_pk_add_f32 v[60:61], v[160:161], v[76:77]
	v_pk_add_f32 v[48:49], v[152:153], v[48:49]
	v_pk_add_f32 v[50:51], v[66:67], v[50:51]
	v_pk_add_f32 v[60:61], v[150:151], v[60:61]
	v_pk_add_f32 v[52:53], v[68:69], v[52:53]
	v_pk_add_f32 v[48:49], v[50:51], v[48:49]
	v_pk_add_f32 v[50:51], v[70:71], v[54:55]
	v_pk_add_f32 v[52:53], v[52:53], v[60:61]
	v_pk_add_f32 v[60:61], v[136:137], v[78:79]
	v_pk_add_f32 v[48:49], v[50:51], v[48:49]
	v_pk_add_f32 v[50:51], v[72:73], v[56:57]
	v_pk_add_f32 v[52:53], v[60:61], v[52:53]
	v_pk_add_f32 v[58:59], v[74:75], v[58:59]
	v_pk_add_f32 v[152:153], v[50:51], v[48:49]
	v_pk_add_f32 v[150:151], v[58:59], v[52:53]
	s_waitcnt lgkmcnt(0)
	s_barrier
; #define AT_QK_LD0(kb_) do { if constexpr (NEGM) { const LAS unsigned char* kbp_ = Kl + (kb_) * KBUF + r32 * KROWB + hi * 16; AT_KLD2(0); __builtin_amdgcn_sched_barrier(0); } } while (0)
; template <int DQK, int DV, int RH, bool NEGM> ...
;     ...
;         for (int t = 0; t < NT; ++t) {
;             const int kb = t & 1;
;             if (t + 1 < NT) AT_GLOAD(t + 1);
;             f32x16 p[RH][2];
;             AT_QK_LD0(kb); AT_QK(kb); AT_VLOAD(vs_cur); AT_SOFTMAX(); AT_PV(vs_cur);
;             if (t + 1 < NT) AT_LSTORE(kb ^ 1, vs_next);
;             __syncthreads();
;             vs_prev = vs_cur; vs_cur = vs_next; vs_next = (vs_next == 2) ? 0 : vs_next + 1;
	ds_read_b128 v[48:51], v169
	ds_read_b128 v[52:55], v169 offset:32
	ds_read_b128 v[116:119], v169 offset:6656
	ds_read_b128 v[120:123], v169 offset:6688
	s_add_i32 m0, s70, 13312
	s_nop 0
	global_load_lds_dwordx4 v241, s[98:99]
	s_add_i32 m0, s73, s74
	global_load_dwordx4 v[112:115], v158, s[100:101] offset:384
	global_load_lds_dwordx4 v242, s[98:99]
	s_add_u32 s98, s98, 0x18000
	s_addc_u32 s99, s99, 0
	s_waitcnt lgkmcnt(3)
	v_mfma_f32_32x32x16_bf16 v[64:79], v[48:51], v[100:103], v[32:47]
	ds_read_b128 v[124:127], v169 offset:64
	ds_read_b128 v[128:131], v169 offset:96
	ds_read_b128 v[132:135], v169 offset:6720
	ds_read_b128 v[136:139], v169 offset:6752
	s_waitcnt lgkmcnt(4)
	v_mfma_f32_32x32x16_bf16 v[64:79], v[52:55], v[96:99], v[64:79]
	v_mfma_f32_32x32x16_bf16 v[48:63], v[116:119], v[100:103], v[32:47]
	v_mfma_f32_32x32x16_bf16 v[48:63], v[120:123], v[96:99], v[48:63]
	s_waitcnt lgkmcnt(1)
	v_mfma_f32_32x32x16_bf16 v[64:79], v[124:127], v[92:95], v[64:79]
	v_mfma_f32_32x32x16_bf16 v[48:63], v[132:135], v[92:95], v[48:63]
	v_mfma_f32_32x32x16_bf16 v[64:79], v[128:131], v[88:91], v[64:79]
	ds_read_b128 v[116:119], v169 offset:128
	ds_read_b128 v[120:123], v169 offset:160
	ds_read_b128 v[128:131], v169 offset:6784
	ds_read_b128 v[176:179], v169 offset:6816
	s_waitcnt lgkmcnt(3)
	v_mfma_f32_32x32x16_bf16 v[48:63], v[136:139], v[88:91], v[48:63]
	v_mfma_f32_32x32x16_bf16 v[64:79], v[116:119], v[84:87], v[64:79]
	ds_read_b128 v[136:139], v170 offset:35840
	ds_read_b128 v[124:127], v170 offset:35872
	s_waitcnt lgkmcnt(3)
	v_mfma_f32_32x32x16_bf16 v[48:63], v[128:131], v[84:87], v[48:63]
	v_mfma_f32_32x32x16_bf16 v[64:79], v[120:123], v[80:83], v[64:79]
	ds_read_b128 v[132:135], v170 offset:35904
	ds_read_b128 v[120:123], v170 offset:35936
	ds_read_b128 v[144:147], v170 offset:40448
	ds_read_b128 v[140:143], v170 offset:40480
	ds_read_b128 v[128:131], v170 offset:40512
	ds_read_b128 v[116:119], v170 offset:40544
	s_waitcnt lgkmcnt(8)
	v_mfma_f32_32x32x16_bf16 v[48:63], v[176:179], v[80:83], v[48:63]
	s_add_i32 s43, s43, 1
	s_nop 3
	v_exp_f32_e32 v160, v64
	v_exp_f32_e32 v161, v65
	v_exp_f32_e32 v64, v66
	v_exp_f32_e32 v65, v67
	v_exp_f32_e32 v68, v68
	v_exp_f32_e32 v69, v69
	v_exp_f32_e32 v66, v70
	v_exp_f32_e32 v67, v71
	v_cvt_pk_bf16_f32 v176, v160, v161
	v_cvt_pk_bf16_f32 v177, v64, v65
	v_cvt_pk_bf16_f32 v178, v68, v69
	v_cvt_pk_bf16_f32 v179, v66, v67
	v_exp_f32_e32 v70, v74
	v_exp_f32_e32 v71, v75
	s_waitcnt lgkmcnt(0)
	v_mfma_f32_32x32x16_bf16 v[16:31], v[136:139], v[176:179], v[16:31]
	v_exp_f32_e32 v136, v72
	v_exp_f32_e32 v137, v73
	v_exp_f32_e32 v74, v76
	v_exp_f32_e32 v75, v77
	v_exp_f32_e32 v72, v78
	v_exp_f32_e32 v73, v79
	v_exp_f32_e32 v76, v48
	v_mfma_f32_32x32x16_bf16 v[0:15], v[144:147], v[176:179], v[0:15]
	v_cvt_pk_bf16_f32 v144, v136, v137
	v_cvt_pk_bf16_f32 v145, v70, v71
	v_cvt_pk_bf16_f32 v146, v74, v75
	v_cvt_pk_bf16_f32 v147, v72, v73
	v_exp_f32_e32 v77, v49
	v_exp_f32_e32 v48, v50
	v_exp_f32_e32 v49, v51
	v_mfma_f32_32x32x16_bf16 v[16:31], v[124:127], v[144:147], v[16:31]
	v_exp_f32_e32 v52, v52
	v_exp_f32_e32 v53, v53
	v_exp_f32_e32 v50, v54
	v_exp_f32_e32 v51, v55
	v_cvt_pk_bf16_f32 v124, v76, v77
	v_cvt_pk_bf16_f32 v125, v48, v49
	v_cvt_pk_bf16_f32 v126, v52, v53
	v_mfma_f32_32x32x16_bf16 v[0:15], v[140:143], v[144:147], v[0:15]
	v_cvt_pk_bf16_f32 v127, v50, v51
	v_exp_f32_e32 v78, v56
	v_exp_f32_e32 v79, v57
	v_exp_f32_e32 v54, v58
	v_exp_f32_e32 v55, v59
	v_exp_f32_e32 v58, v60
	v_exp_f32_e32 v59, v61
	v_mfma_f32_32x32x16_bf16 v[16:31], v[132:135], v[124:127], v[16:31]
	v_exp_f32_e32 v56, v62
	v_exp_f32_e32 v57, v63
	v_cvt_pk_bf16_f32 v60, v78, v79
	v_cvt_pk_bf16_f32 v61, v54, v55
	v_cvt_pk_bf16_f32 v62, v58, v59
	v_cvt_pk_bf16_f32 v63, v56, v57
	v_mfma_f32_32x32x16_bf16 v[0:15], v[128:131], v[124:127], v[0:15]
	v_mfma_f32_32x32x16_bf16 v[16:31], v[120:123], v[60:63], v[16:31]
	v_mfma_f32_32x32x16_bf16 v[0:15], v[116:119], v[60:63], v[0:15]
	s_waitcnt vmcnt(0)
	ds_write2_b64 v247, v[112:113], v[114:115] offset1:2
	v_pk_add_f32 v[48:49], v[64:65], v[48:49]
	v_pk_add_f32 v[60:61], v[160:161], v[76:77]
	v_pk_add_f32 v[48:49], v[152:153], v[48:49]
	v_pk_add_f32 v[50:51], v[66:67], v[50:51]
	v_pk_add_f32 v[60:61], v[150:151], v[60:61]
	v_pk_add_f32 v[52:53], v[68:69], v[52:53]
	v_pk_add_f32 v[48:49], v[50:51], v[48:49]
	v_pk_add_f32 v[50:51], v[70:71], v[54:55]
	v_pk_add_f32 v[52:53], v[52:53], v[60:61]
	v_pk_add_f32 v[60:61], v[136:137], v[78:79]
	v_pk_add_f32 v[48:49], v[50:51], v[48:49]
	v_pk_add_f32 v[50:51], v[72:73], v[56:57]
	v_pk_add_f32 v[52:53], v[60:61], v[52:53]
	v_pk_add_f32 v[58:59], v[74:75], v[58:59]
	v_pk_add_f32 v[152:153], v[50:51], v[48:49]
	v_pk_add_f32 v[150:151], v[58:59], v[52:53]
	s_waitcnt lgkmcnt(0)
	s_barrier
; #define AT_QK_LD0(kb_) do { if constexpr (NEGM) { const LAS unsigned char* kbp_ = Kl + (kb_) * KBUF + r32 * KROWB + hi * 16; AT_KLD2(0); __builtin_amdgcn_sched_barrier(0); } } while (0)
; template <int DQK, int DV, int RH, bool NEGM> ...
;     ...
;         for (int t = 0; t < NT; ++t) {
;             const int kb = t & 1;
;             if (t + 1 < NT) AT_GLOAD(t + 1);
;             f32x16 p[RH][2];
;             AT_QK_LD0(kb); AT_QK(kb); AT_VLOAD(vs_cur); AT_SOFTMAX(); AT_PV(vs_cur);
;             if (t + 1 < NT) AT_LSTORE(kb ^ 1, vs_next);
;             __syncthreads();
;             vs_prev = vs_cur; vs_cur = vs_next; vs_next = (vs_next == 2) ? 0 : vs_next + 1;
	ds_read_b128 v[48:51], v169 offset:13312
	ds_read_b128 v[52:55], v169 offset:13344
	ds_read_b128 v[116:119], v169 offset:19968
	ds_read_b128 v[120:123], v169 offset:20000
	s_mov_b32 m0, s70
	s_nop 0
	global_load_lds_dwordx4 v241, s[98:99]
	s_mov_b32 m0, s73
	global_load_dwordx4 v[112:115], v158, s[100:101] offset:512
	global_load_lds_dwordx4 v242, s[98:99]
	s_add_u32 s98, s98, 0x18000
	s_addc_u32 s99, s99, 0
	s_waitcnt lgkmcnt(3)
	v_mfma_f32_32x32x16_bf16 v[64:79], v[48:51], v[100:103], v[32:47]
	ds_read_b128 v[124:127], v169 offset:13376
	ds_read_b128 v[128:131], v169 offset:13408
	ds_read_b128 v[132:135], v169 offset:20032
	ds_read_b128 v[136:139], v169 offset:20064
	s_waitcnt lgkmcnt(4)
	v_mfma_f32_32x32x16_bf16 v[64:79], v[52:55], v[96:99], v[64:79]
	v_mfma_f32_32x32x16_bf16 v[48:63], v[116:119], v[100:103], v[32:47]
	v_mfma_f32_32x32x16_bf16 v[48:63], v[120:123], v[96:99], v[48:63]
	s_waitcnt lgkmcnt(1)
	v_mfma_f32_32x32x16_bf16 v[64:79], v[124:127], v[92:95], v[64:79]
	v_mfma_f32_32x32x16_bf16 v[48:63], v[132:135], v[92:95], v[48:63]
	v_mfma_f32_32x32x16_bf16 v[64:79], v[128:131], v[88:91], v[64:79]
	ds_read_b128 v[116:119], v169 offset:13440
	ds_read_b128 v[120:123], v169 offset:13472
	ds_read_b128 v[128:131], v169 offset:20096
	ds_read_b128 v[176:179], v169 offset:20128
	s_waitcnt lgkmcnt(3)
	v_mfma_f32_32x32x16_bf16 v[48:63], v[136:139], v[88:91], v[48:63]
	v_mfma_f32_32x32x16_bf16 v[64:79], v[116:119], v[84:87], v[64:79]
	ds_read_b128 v[136:139], v170 offset:45056
	ds_read_b128 v[124:127], v170 offset:45088
	s_waitcnt lgkmcnt(3)
	v_mfma_f32_32x32x16_bf16 v[48:63], v[128:131], v[84:87], v[48:63]
	v_mfma_f32_32x32x16_bf16 v[64:79], v[120:123], v[80:83], v[64:79]
	ds_read_b128 v[132:135], v170 offset:45120
	ds_read_b128 v[120:123], v170 offset:45152
	ds_read_b128 v[144:147], v170 offset:49664
	ds_read_b128 v[140:143], v170 offset:49696
	ds_read_b128 v[128:131], v170 offset:49728
	ds_read_b128 v[116:119], v170 offset:49760
	s_waitcnt lgkmcnt(8)
	v_mfma_f32_32x32x16_bf16 v[48:63], v[176:179], v[80:83], v[48:63]
	s_add_i32 s43, s43, 1
	s_nop 3
	v_exp_f32_e32 v160, v64
	v_exp_f32_e32 v161, v65
	v_exp_f32_e32 v64, v66
	v_exp_f32_e32 v65, v67
	v_exp_f32_e32 v68, v68
	v_exp_f32_e32 v69, v69
	v_exp_f32_e32 v66, v70
	v_exp_f32_e32 v67, v71
	v_cvt_pk_bf16_f32 v176, v160, v161
	v_cvt_pk_bf16_f32 v177, v64, v65
	v_cvt_pk_bf16_f32 v178, v68, v69
	v_cvt_pk_bf16_f32 v179, v66, v67
	v_exp_f32_e32 v70, v74
	v_exp_f32_e32 v71, v75
	s_waitcnt lgkmcnt(0)
	v_mfma_f32_32x32x16_bf16 v[16:31], v[136:139], v[176:179], v[16:31]
	v_exp_f32_e32 v136, v72
	v_exp_f32_e32 v137, v73
	v_exp_f32_e32 v74, v76
	v_exp_f32_e32 v75, v77
	v_exp_f32_e32 v72, v78
	v_exp_f32_e32 v73, v79
	v_exp_f32_e32 v76, v48
	v_mfma_f32_32x32x16_bf16 v[0:15], v[144:147], v[176:179], v[0:15]
	v_cvt_pk_bf16_f32 v144, v136, v137
	v_cvt_pk_bf16_f32 v145, v70, v71
	v_cvt_pk_bf16_f32 v146, v74, v75
	v_cvt_pk_bf16_f32 v147, v72, v73
	v_exp_f32_e32 v77, v49
	v_exp_f32_e32 v48, v50
	v_exp_f32_e32 v49, v51
	v_mfma_f32_32x32x16_bf16 v[16:31], v[124:127], v[144:147], v[16:31]
	v_exp_f32_e32 v52, v52
	v_exp_f32_e32 v53, v53
	v_exp_f32_e32 v50, v54
	v_exp_f32_e32 v51, v55
	v_cvt_pk_bf16_f32 v124, v76, v77
	v_cvt_pk_bf16_f32 v125, v48, v49
	v_cvt_pk_bf16_f32 v126, v52, v53
	v_mfma_f32_32x32x16_bf16 v[0:15], v[140:143], v[144:147], v[0:15]
	v_cvt_pk_bf16_f32 v127, v50, v51
	v_exp_f32_e32 v78, v56
	v_exp_f32_e32 v79, v57
	v_exp_f32_e32 v54, v58
	v_exp_f32_e32 v55, v59
	v_exp_f32_e32 v58, v60
	v_exp_f32_e32 v59, v61
	v_mfma_f32_32x32x16_bf16 v[16:31], v[132:135], v[124:127], v[16:31]
	v_exp_f32_e32 v56, v62
	v_exp_f32_e32 v57, v63
	v_cvt_pk_bf16_f32 v60, v78, v79
	v_cvt_pk_bf16_f32 v61, v54, v55
	v_cvt_pk_bf16_f32 v62, v58, v59
	v_cvt_pk_bf16_f32 v63, v56, v57
	v_mfma_f32_32x32x16_bf16 v[0:15], v[128:131], v[124:127], v[0:15]
	v_mfma_f32_32x32x16_bf16 v[16:31], v[120:123], v[60:63], v[16:31]
	v_mfma_f32_32x32x16_bf16 v[0:15], v[116:119], v[60:63], v[0:15]
	s_waitcnt vmcnt(0)
	ds_write2_b64 v243, v[112:113], v[114:115] offset1:2
	v_pk_add_f32 v[48:49], v[64:65], v[48:49]
	v_pk_add_f32 v[60:61], v[160:161], v[76:77]
	v_pk_add_f32 v[48:49], v[152:153], v[48:49]
	v_pk_add_f32 v[50:51], v[66:67], v[50:51]
	v_pk_add_f32 v[60:61], v[150:151], v[60:61]
	v_pk_add_f32 v[52:53], v[68:69], v[52:53]
	v_pk_add_f32 v[48:49], v[50:51], v[48:49]
	v_pk_add_f32 v[50:51], v[70:71], v[54:55]
	v_pk_add_f32 v[52:53], v[52:53], v[60:61]
	v_pk_add_f32 v[60:61], v[136:137], v[78:79]
	v_pk_add_f32 v[48:49], v[50:51], v[48:49]
	v_pk_add_f32 v[50:51], v[72:73], v[56:57]
	v_pk_add_f32 v[52:53], v[60:61], v[52:53]
	v_pk_add_f32 v[58:59], v[74:75], v[58:59]
	v_pk_add_f32 v[152:153], v[50:51], v[48:49]
	v_pk_add_f32 v[150:151], v[58:59], v[52:53]
	s_waitcnt lgkmcnt(0)
	s_barrier
; #define AT_QK_LD0(kb_) do { if constexpr (NEGM) { const LAS unsigned char* kbp_ = Kl + (kb_) * KBUF + r32 * KROWB + hi * 16; AT_KLD2(0); __builtin_amdgcn_sched_barrier(0); } } while (0)
; template <int DQK, int DV, int RH, bool NEGM> ...
;     ...
;         for (int t = 0; t < NT; ++t) {
;             const int kb = t & 1;
;             if (t + 1 < NT) AT_GLOAD(t + 1);
;             f32x16 p[RH][2];
;             AT_QK_LD0(kb); AT_QK(kb); AT_VLOAD(vs_cur); AT_SOFTMAX(); AT_PV(vs_cur);
;             if (t + 1 < NT) AT_LSTORE(kb ^ 1, vs_next);
;             __syncthreads();
;             vs_prev = vs_cur; vs_cur = vs_next; vs_next = (vs_next == 2) ? 0 : vs_next + 1;
	ds_read_b128 v[48:51], v169
	ds_read_b128 v[52:55], v169 offset:32
	ds_read_b128 v[116:119], v169 offset:6656
	ds_read_b128 v[120:123], v169 offset:6688
	s_add_i32 m0, s70, 13312
	s_nop 0
	global_load_lds_dwordx4 v241, s[98:99]
	s_add_i32 m0, s73, s74
	global_load_dwordx4 v[112:115], v158, s[100:101] offset:640
	global_load_lds_dwordx4 v242, s[98:99]
	s_add_u32 s98, s98, 0x18000
	s_addc_u32 s99, s99, 0
	s_waitcnt lgkmcnt(3)
	v_mfma_f32_32x32x16_bf16 v[64:79], v[48:51], v[100:103], v[32:47]
	ds_read_b128 v[124:127], v169 offset:64
	ds_read_b128 v[128:131], v169 offset:96
	ds_read_b128 v[132:135], v169 offset:6720
	ds_read_b128 v[136:139], v169 offset:6752
	s_waitcnt lgkmcnt(4)
	v_mfma_f32_32x32x16_bf16 v[64:79], v[52:55], v[96:99], v[64:79]
	v_mfma_f32_32x32x16_bf16 v[48:63], v[116:119], v[100:103], v[32:47]
	v_mfma_f32_32x32x16_bf16 v[48:63], v[120:123], v[96:99], v[48:63]
	s_waitcnt lgkmcnt(1)
	v_mfma_f32_32x32x16_bf16 v[64:79], v[124:127], v[92:95], v[64:79]
	v_mfma_f32_32x32x16_bf16 v[48:63], v[132:135], v[92:95], v[48:63]
	v_mfma_f32_32x32x16_bf16 v[64:79], v[128:131], v[88:91], v[64:79]
	ds_read_b128 v[116:119], v169 offset:128
	ds_read_b128 v[120:123], v169 offset:160
	ds_read_b128 v[128:131], v169 offset:6784
	ds_read_b128 v[176:179], v169 offset:6816
	s_waitcnt lgkmcnt(3)
	v_mfma_f32_32x32x16_bf16 v[48:63], v[136:139], v[88:91], v[48:63]
	v_mfma_f32_32x32x16_bf16 v[64:79], v[116:119], v[84:87], v[64:79]
	ds_read_b128 v[136:139], v170 offset:26624
	ds_read_b128 v[124:127], v170 offset:26656
	s_waitcnt lgkmcnt(3)
	v_mfma_f32_32x32x16_bf16 v[48:63], v[128:131], v[84:87], v[48:63]
	v_mfma_f32_32x32x16_bf16 v[64:79], v[120:123], v[80:83], v[64:79]
	ds_read_b128 v[132:135], v170 offset:26688
	ds_read_b128 v[120:123], v170 offset:26720
	ds_read_b128 v[144:147], v170 offset:31232
	ds_read_b128 v[140:143], v170 offset:31264
	ds_read_b128 v[128:131], v170 offset:31296
	ds_read_b128 v[116:119], v170 offset:31328
	s_waitcnt lgkmcnt(8)
	v_mfma_f32_32x32x16_bf16 v[48:63], v[176:179], v[80:83], v[48:63]
	s_add_i32 s43, s43, 1
	s_nop 3
	v_exp_f32_e32 v160, v64
	v_exp_f32_e32 v161, v65
	v_exp_f32_e32 v64, v66
	v_exp_f32_e32 v65, v67
	v_exp_f32_e32 v68, v68
	v_exp_f32_e32 v69, v69
	v_exp_f32_e32 v66, v70
	v_exp_f32_e32 v67, v71
	v_cvt_pk_bf16_f32 v176, v160, v161
	v_cvt_pk_bf16_f32 v177, v64, v65
	v_cvt_pk_bf16_f32 v178, v68, v69
	v_cvt_pk_bf16_f32 v179, v66, v67
	v_exp_f32_e32 v70, v74
	v_exp_f32_e32 v71, v75
	s_waitcnt lgkmcnt(0)
	v_mfma_f32_32x32x16_bf16 v[16:31], v[136:139], v[176:179], v[16:31]
	v_exp_f32_e32 v136, v72
	v_exp_f32_e32 v137, v73
	v_exp_f32_e32 v74, v76
	v_exp_f32_e32 v75, v77
	v_exp_f32_e32 v72, v78
	v_exp_f32_e32 v73, v79
	v_exp_f32_e32 v76, v48
	v_mfma_f32_32x32x16_bf16 v[0:15], v[144:147], v[176:179], v[0:15]
	v_cvt_pk_bf16_f32 v144, v136, v137
	v_cvt_pk_bf16_f32 v145, v70, v71
	v_cvt_pk_bf16_f32 v146, v74, v75
	v_cvt_pk_bf16_f32 v147, v72, v73
	v_exp_f32_e32 v77, v49
	v_exp_f32_e32 v48, v50
	v_exp_f32_e32 v49, v51
	v_mfma_f32_32x32x16_bf16 v[16:31], v[124:127], v[144:147], v[16:31]
	v_exp_f32_e32 v52, v52
	v_exp_f32_e32 v53, v53
	v_exp_f32_e32 v50, v54
	v_exp_f32_e32 v51, v55
	v_cvt_pk_bf16_f32 v124, v76, v77
	v_cvt_pk_bf16_f32 v125, v48, v49
	v_cvt_pk_bf16_f32 v126, v52, v53
	v_mfma_f32_32x32x16_bf16 v[0:15], v[140:143], v[144:147], v[0:15]
	v_cvt_pk_bf16_f32 v127, v50, v51
	v_exp_f32_e32 v78, v56
	v_exp_f32_e32 v79, v57
	v_exp_f32_e32 v54, v58
	v_exp_f32_e32 v55, v59
	v_exp_f32_e32 v58, v60
	v_exp_f32_e32 v59, v61
	v_mfma_f32_32x32x16_bf16 v[16:31], v[132:135], v[124:127], v[16:31]
	v_exp_f32_e32 v56, v62
	v_exp_f32_e32 v57, v63
	v_cvt_pk_bf16_f32 v60, v78, v79
	v_cvt_pk_bf16_f32 v61, v54, v55
	v_cvt_pk_bf16_f32 v62, v58, v59
	v_cvt_pk_bf16_f32 v63, v56, v57
	v_mfma_f32_32x32x16_bf16 v[0:15], v[128:131], v[124:127], v[0:15]
	v_mfma_f32_32x32x16_bf16 v[16:31], v[120:123], v[60:63], v[16:31]
	v_mfma_f32_32x32x16_bf16 v[0:15], v[116:119], v[60:63], v[0:15]
	s_waitcnt vmcnt(0)
	ds_write2_b64 v246, v[112:113], v[114:115] offset1:2
	v_pk_add_f32 v[48:49], v[64:65], v[48:49]
	v_pk_add_f32 v[60:61], v[160:161], v[76:77]
	v_pk_add_f32 v[48:49], v[152:153], v[48:49]
	v_pk_add_f32 v[50:51], v[66:67], v[50:51]
	v_pk_add_f32 v[60:61], v[150:151], v[60:61]
	v_pk_add_f32 v[52:53], v[68:69], v[52:53]
	v_pk_add_f32 v[48:49], v[50:51], v[48:49]
	v_pk_add_f32 v[50:51], v[70:71], v[54:55]
	v_pk_add_f32 v[52:53], v[52:53], v[60:61]
	v_pk_add_f32 v[60:61], v[136:137], v[78:79]
	v_pk_add_f32 v[48:49], v[50:51], v[48:49]
	v_pk_add_f32 v[50:51], v[72:73], v[56:57]
	v_pk_add_f32 v[52:53], v[60:61], v[52:53]
	v_pk_add_f32 v[58:59], v[74:75], v[58:59]
	v_pk_add_f32 v[152:153], v[50:51], v[48:49]
	v_pk_add_f32 v[150:151], v[58:59], v[52:53]
	v_max3_f32 v148, v150, v151, v152
	v_max_f32_e32 v148, v148, v153
	v_cmp_nge_f32_e32 vcc, 0x49800000, v148
	s_cbranch_vccnz .Lmla_renorm
.Lmla_renorm_back:
	s_waitcnt lgkmcnt(0)
	s_barrier
	s_add_u32 s100, s100, 0x300
	s_addc_u32 s101, s101, 0
	s_branch .Lmla_loop
